# SEL: next item's Q rows requested before the key loop into the idle K/V staging registers when the K/V block stays
# baseline (speedup 1.0000x reference)
.LBB0_251:
	s_waitcnt lgkmcnt(1)
	v_sub_u32_e32 v238, s48, v84
	s_mov_b32 s32, 0
	s_and_b64 vcc, exec, s[88:89]
	s_cbranch_vccnz .Lsel_nqp
	s_ashr_i32 s67, s66, 31
	s_lshl_b64 s[68:69], s[66:67], 22
	v_bfe_u32 v158, v217, 2, 29
	v_lshlrev_b64 v[148:149], 8, v[158:159]
	v_bfe_u32 v158, v216, 2, 29
	v_lshl_add_u64 v[150:151], v[184:185], 0, s[68:69]
	v_lshlrev_b64 v[152:153], 8, v[158:159]
	v_lshl_add_u64 v[148:149], v[150:151], 0, v[148:149]
	v_lshl_add_u64 v[152:153], v[150:151], 0, v[152:153]
	global_load_dwordx4 v[32:35], v[148:149], off
	global_load_dwordx4 v[36:39], v[148:149], off offset:64
	global_load_dwordx4 v[40:43], v[148:149], off offset:128
	global_load_dwordx4 v[44:47], v[148:149], off offset:192
	global_load_dwordx4 v[48:51], v[152:153], off
	global_load_dwordx4 v[52:55], v[152:153], off offset:64
	global_load_dwordx4 v[60:63], v[152:153], off offset:128
	global_load_dwordx4 v[64:67], v[152:153], off offset:192
	s_mov_b32 s32, 1
.Lsel_nqp:
	s_branch .LBB0_253
.LBB0_252:
	v_mov_b32_e32 v236, 0
	s_mov_b64 s[88:89], -1
	v_mov_b32_e32 v235, v213
	v_mov_b32_e32 v238, v191
	s_mov_b32 s50, s14
	s_mov_b32 s66, s10
	v_mov_b32_e32 v237, 0

.LBB0_256:
	s_or_b64 exec, exec, s[72:73]
	s_andn2_b64 vcc, exec, s[74:75]
	s_cbranch_vccnz .LBB0_258
	s_cmp_eq_u32 s32, 1
	s_cbranch_scc0 .Lsel_qload
	s_waitcnt vmcnt(0)
	v_cmp_ne_u32_e32 vcc, -1, v236
	v_or_b32_e32 v148, 0x80000000, v236
	v_cmp_ne_u32_e64 s[68:69], -1, v237
	v_or_b32_e32 v149, 0x80000000, v237
	v_cndmask_b32_e32 v236, 0, v148, vcc
	v_cndmask_b32_e64 v237, 0, v149, s[68:69]
	v_mov_b32_e32 v0, v32
	v_mov_b32_e32 v1, v33
	v_mov_b32_e32 v2, v34
	v_mov_b32_e32 v3, v35
	v_mov_b32_e32 v4, v36
	v_mov_b32_e32 v5, v37
	v_mov_b32_e32 v6, v38
	v_mov_b32_e32 v7, v39
	v_mov_b32_e32 v8, v40
	v_mov_b32_e32 v9, v41
	v_mov_b32_e32 v10, v42
	v_mov_b32_e32 v11, v43
	v_mov_b32_e32 v12, v44
	v_mov_b32_e32 v13, v45
	v_mov_b32_e32 v14, v46
	v_mov_b32_e32 v15, v47
	v_mov_b32_e32 v16, v48
	v_mov_b32_e32 v17, v49
	v_mov_b32_e32 v18, v50
	v_mov_b32_e32 v19, v51
	v_mov_b32_e32 v20, v52
	v_mov_b32_e32 v21, v53
	v_mov_b32_e32 v22, v54
	v_mov_b32_e32 v23, v55
	v_mov_b32_e32 v24, v60
	v_mov_b32_e32 v25, v61
	v_mov_b32_e32 v26, v62
	v_mov_b32_e32 v27, v63
	v_mov_b32_e32 v28, v64
	v_mov_b32_e32 v29, v65
	v_mov_b32_e32 v30, v66
	v_mov_b32_e32 v31, v67
	s_branch .LBB0_258
.Lsel_qload:
	s_ashr_i32 s67, s66, 31
	v_bfe_u32 v158, v217, 2, 29
	s_lshl_b64 s[68:69], s[66:67], 22
	s_waitcnt vmcnt(7)
	v_lshlrev_b64 v[0:1], 8, v[158:159]
	v_bfe_u32 v158, v216, 2, 29
	s_waitcnt vmcnt(3)
	v_lshl_add_u64 v[16:17], v[184:185], 0, s[68:69]
	v_lshlrev_b64 v[18:19], 8, v[158:159]
	v_lshl_add_u64 v[12:13], v[16:17], 0, v[0:1]
	s_waitcnt vmcnt(0)
	v_cmp_ne_u32_e32 vcc, -1, v236
	v_or_b32_e32 v148, 0x80000000, v236
	v_cmp_ne_u32_e64 s[68:69], -1, v237
	v_or_b32_e32 v149, 0x80000000, v237
	v_cndmask_b32_e32 v236, 0, v148, vcc
	v_cndmask_b32_e64 v237, 0, v149, s[68:69]
	v_lshl_add_u64 v[28:29], v[16:17], 0, v[18:19]
	global_load_dwordx4 v[0:3], v[12:13], off
	global_load_dwordx4 v[4:7], v[12:13], off offset:64
	global_load_dwordx4 v[8:11], v[12:13], off offset:128
	s_nop 0
	global_load_dwordx4 v[12:15], v[12:13], off offset:192
	s_nop 0
	global_load_dwordx4 v[16:19], v[28:29], off
	global_load_dwordx4 v[20:23], v[28:29], off offset:64
	global_load_dwordx4 v[24:27], v[28:29], off offset:128
	s_nop 0
	global_load_dwordx4 v[28:31], v[28:29], off offset:192
